# P5: workgroups 0-31 run their split-K slab unit before the y_a / y_b units
# speedup vs baseline: 1.0086x; 1.0005x over previous
;     __device__ bool next(int i, Unit& u) const {
;         if (i < nZ * nmain) {
;             const int ti = (nZ == 2) ? (i >> 1) : i;
;             int wgid = ti * G + c; { const int q = nwg / NXCD, r = nwg % NXCD, xcd = wgid % NXCD, off = wgid / NXCD; wgid = (xcd < r ? xcd * (q + 1) : r * (q + 1) + (xcd - r) * q) + off; }
;             const int nig = WGM * nN, gid = wgid / nig, fm = gid * WGM, gsz = (nM - fm) < WGM ? (nM - fm) : WGM;
;             u.pm = fm + ((wgid % nig) % gsz); u.pn = (wgid % nig) / gsz; u.z = (nZ == 2) ? (i & 1) : 0; u.kt0 = 0; u.nkt = ntFull; return true;
;         }
;         if (!splitS) return false;
;         const int e = (i - nZ * nmain) * G + c; if (e >= nN * nZ * splitS) return false;
;         u.pm = nM; u.pn = e % nN; const int zs = e / nN; u.z = (nZ == 2) ? (zs & 1) : 0; u.kt0 = ((nZ == 2) ? (zs >> 1) : zs) * 4; u.nkt = 4; return true;
.LBB0_480:
	s_cmp_lt_u32 s74, 32
	s_cselect_b32 s75, 0, s75
	v_mov_b32_e32 v0, v209
	s_cmp_lt_i32 s75, 1
	v_readfirstlane_b32 s12, v0
	s_mov_b64 s[10:11], -1
	s_cbranch_scc0 .LBB0_483
	s_mul_i32 s4, s75, s57
	s_sub_i32 s5, s74, s4
	s_mov_b64 s[10:11], 0
	s_cmp_gt_i32 s5, 31
	s_mov_b64 s[8:9], 0
	s_cbranch_scc1 .LBB0_483
	s_ashr_i32 s4, s5, 31
	s_lshr_b32 s4, s4, 30
	s_add_i32 s4, s5, s4
	s_ashr_i32 s8, s4, 2
	s_and_b32 s4, s4, -4
	s_sub_i32 s66, s5, s4
	s_lshl_b32 s4, s8, 1
	s_and_b32 s16, s8, 1
	s_and_b32 s4, s4, -4
	s_mov_b32 s19, 4
	s_mov_b32 s18, 64
	s_mov_b64 s[8:9], -1

;     __device__ bool next(int i, Unit& u) const {
;         if (i < nZ * nmain) {
;             const int ti = (nZ == 2) ? (i >> 1) : i;
;             int wgid = ti * G + c; { const int q = nwg / NXCD, r = nwg % NXCD, xcd = wgid % NXCD, off = wgid / NXCD; wgid = (xcd < r ? xcd * (q + 1) : r * (q + 1) + (xcd - r) * q) + off; }
;             const int nig = WGM * nN, gid = wgid / nig, fm = gid * WGM, gsz = (nM - fm) < WGM ? (nM - fm) : WGM;
;             u.pm = fm + ((wgid % nig) % gsz); u.pn = (wgid % nig) / gsz; u.z = (nZ == 2) ? (i & 1) : 0; u.kt0 = 0; u.nkt = ntFull; return true;
;         }
;         if (!splitS) return false;
;         const int e = (i - nZ * nmain) * G + c; if (e >= nN * nZ * splitS) return false;
;         u.pm = nM; u.pn = e % nN; const int zs = e / nN; u.z = (nZ == 2) ? (zs & 1) : 0; u.kt0 = ((nZ == 2) ? (zs >> 1) : zs) * 4; u.nkt = 4; return true;
.LBB0_495:
	s_add_i32 s90, s90, 1
	s_mov_b32 s48, s90
	s_cmp_lt_u32 s74, 32
	s_cbranch_scc0 .Lp5o_norm
	s_add_i32 s48, s90, -1
	s_mov_b64 s[6:7], -1
	s_cmp_le_u32 s90, 2
	s_cbranch_scc1 .LBB0_498
	s_mov_b64 s[6:7], 0
	s_mov_b64 s[60:61], 0
	s_branch .LBB0_498
.Lp5o_norm:
	s_cmp_ge_i32 s90, s75
	s_mov_b64 s[6:7], -1
	s_cbranch_scc0 .LBB0_498
	s_sub_i32 s5, s90, s75
	s_mul_i32 s5, s5, s57
	s_add_i32 s5, s5, s74
	s_mov_b64 s[6:7], 0
	s_cmp_gt_i32 s5, 31
	s_mov_b64 s[60:61], 0
	s_cbranch_scc1 .LBB0_498
	s_ashr_i32 s14, s5, 31
	s_lshr_b32 s14, s14, 30
	s_add_i32 s14, s5, s14
	s_ashr_i32 s15, s14, 2
	s_and_b32 s14, s14, -4
	s_sub_i32 s58, s5, s14
	s_lshl_b32 s5, s15, 1
	s_and_b32 s91, s15, 1
	s_and_b32 s14, s5, -4
	s_mov_b32 s92, 4
	s_mov_b32 s93, 64
	s_mov_b64 s[60:61], -1
.LBB0_498:
	s_andn2_b64 vcc, exec, s[6:7]
	s_cbranch_vccnz .LBB0_504
	s_lshr_b32 s5, s48, 1
	s_mul_i32 s5, s5, s57
	s_add_i32 s6, s5, s74
	s_ashr_i32 s5, s6, 31
	s_lshr_b32 s5, s5, 29
	s_add_i32 s5, s6, s5
	s_and_b32 s7, s5, -8
	s_sub_i32 s14, s6, s7
	s_cmp_gt_i32 s14, -1
	s_mov_b64 s[6:7], -1
	s_cbranch_scc0 .LBB0_501
	s_lshl_b32 s15, s14, 5
	s_mov_b64 s[6:7], 0

;     __device__ bool next(int i, Unit& u) const {
;     ...
;             int wgid = ti * G + c; { const int q = nwg / NXCD, r = nwg % NXCD, xcd = wgid % NXCD, off = wgid / NXCD; wgid = (xcd < r ? xcd * (q + 1) : r * (q + 1) + (xcd - r) * q) + off; }
;             const int nig = WGM * nN, gid = wgid / nig, fm = gid * WGM, gsz = (nM - fm) < WGM ? (nM - fm) : WGM;
;             u.pm = fm + ((wgid % nig) % gsz); u.pn = (wgid % nig) / gsz; u.z = (nZ == 2) ? (i & 1) : 0; u.kt0 = 0; u.nkt = ntFull; return true;
.LBB0_503:
	s_ashr_i32 s5, s5, 3
	s_add_i32 s5, s15, s5
	s_ashr_i32 s6, s5, 31
	s_lshr_b32 s6, s6, 27
	s_add_i32 s6, s5, s6
	s_ashr_i32 s7, s6, 5
	s_lshl_b32 s7, s7, 3
	s_sub_i32 s14, 64, s7
	s_min_i32 s15, s14, 8
	s_abs_i32 s21, s15
	v_cvt_f32_u32_e32 v0, s21
	s_sub_i32 s24, 0, s21
	s_andn2_b32 s6, s6, 31
	s_sub_i32 s5, s5, s6
	v_rcp_iflag_f32_e32 v0, v0
	s_abs_i32 s6, s5
	s_xor_b32 s23, s5, s15
	s_ashr_i32 s23, s23, 31
	v_mul_f32_e32 v0, 0x4f7ffffe, v0
	v_cvt_u32_f32_e32 v0, v0
	s_mov_b32 s14, 0
	s_mov_b32 s92, 16
	s_mov_b64 s[60:61], -1
	v_readfirstlane_b32 s25, v0
	s_mul_i32 s24, s24, s25
	s_mul_hi_u32 s24, s25, s24
	s_add_i32 s25, s25, s24
	s_mul_hi_u32 s24, s6, s25
	s_mul_i32 s25, s24, s21
	s_sub_i32 s6, s6, s25
	s_add_i32 s34, s24, 1
	s_sub_i32 s25, s6, s21
	s_cmp_ge_u32 s6, s21
	s_cselect_b32 s24, s34, s24
	s_cselect_b32 s6, s25, s6
	s_add_i32 s25, s24, 1
	s_cmp_ge_u32 s6, s21
	s_cselect_b32 s6, s25, s24
	s_xor_b32 s6, s6, s23
	s_sub_i32 s58, s6, s23
	s_mul_i32 s6, s58, s15
	s_sub_i32 s5, s5, s6
	s_add_i32 s93, s7, s5
	s_and_b32 s91, s48, 1
